# combined: hand-written scan consumer loop + producer no longer waits on just-issued loads + P9 touches its 16 Y rows ahead + attention K/V staging moved under the PV MFMAs
# speedup vs baseline: 1.0064x; 1.0064x over previous
; __device__ __forceinline__ void finishSM(f32x16& p0, f32x16& p1, float alpha, float& l_reg, bf16x8& pa0, bf16x8& pa1, bf16x8& pa2, bf16x8& pa3) {
; #pragma unroll
;   for (int r = 0; r < 16; ++r) p1[r] = __builtin_amdgcn_exp2f(p1[r]);
;   typedef float f2_t __attribute__((ext_vector_type(2)));
;   f2_t s2a = {p0[0], p0[1]}, s2b = {p1[0], p1[1]};
; #pragma unroll
;   for (int r = 2; r < 16; r += 2) { s2a += (f2_t){p0[r], p0[r + 1]}; s2b += (f2_t){p1[r], p1[r + 1]}; }
;   s2a += s2b; float ps = s2a.x + s2a.y;
;   { auto rr = __builtin_amdgcn_permlane32_swap(__float_as_uint(ps), __float_as_uint(ps), false, false);
;     ps = __uint_as_float(rr[0]) + __uint_as_float(rr[1]); }
;   l_reg = l_reg * alpha + ps;
;     ...
;   PK4(p0, 0, pa0); PK4(p0, 8, pa1); PK4(p1, 0, pa2); PK4(p1, 8, pa3);
;     ...
; }
; __device__ __forceinline__ void qkt(f32x16& p0, f32x16& p1, const char* Ks, const bf16x8* qr, int r32, int hi, float m_reg) {
; #pragma unroll
;   for (int r = 0; r < 16; ++r) { p0[r] = -m_reg; p1[r] = -m_reg; }
; #pragma unroll
;   for (int d0 = 0; d0 < 6; ++d0) { int cb = (d0 * 16 + hi * 8) * 2;
;     bf16x8 b0 = *reinterpret_cast<const bf16x8*>(Ks + KSWZ(r32, cb));
;     bf16x8 b1 = *reinterpret_cast<const bf16x8*>(Ks + KSWZ(32 + r32, cb));
;     p0 = __builtin_amdgcn_mfma_f32_32x32x16_bf16(b0, qr[d0], p0, 0, 0, 0);
;     p1 = __builtin_amdgcn_mfma_f32_32x32x16_bf16(b1, qr[d0], p1, 0, 0, 0); }
; }
; __device__ __forceinline__ int v_st(int k, int c) { const int kk = (k & ~0xC) | ((k & 4) << 1) | ((k & 8) >> 1); return ((kk >> 3) * 4 + (c >> 5)) * 512 + ((kk & 7) * 32 + (c & 31)) * 2; }
; __device__ __forceinline__ int v_rd_base(int lane) { return ((lane & 3) << 3) | (((lane >> 2) & 3) << 6) | (((lane >> 4) & 1) << 5) | (((lane >> 5) & 1) << 8); }
; template <int OFF> __device__ __forceinline__ s16x4 tr_read(int vb) {
;   s16x4 r; asm volatile("ds_read_b64_tr_b16 %0, %1 offset:%2" : "=&v"(r) : "v"(vb), "i"(OFF) : "memory"); return r;
; }
; template <int D0> __device__ __forceinline__ void pv_one(f32x16& od, int vb, bf16x8 pa0, bf16x8 pa1, bf16x8 pa2, bf16x8 pa3) {
;   const s16x4 l0 = tr_read<v_rd_off(D0, 0, 0)>(vb), h0 = tr_read<v_rd_off(D0, 0, 1)>(vb), l1 = tr_read<v_rd_off(D0, 1, 0)>(vb), h1 = tr_read<v_rd_off(D0, 1, 1)>(vb);
.LBB0_667:
	s_mov_b32 s24, s90
	s_mov_b32 s90, s4
	s_add_i32 s4, s24, 0
	v_add_u32_e32 v64, s4, v150
	ds_read_b128 v[158:161], v64 offset:49152
	ds_read_b128 v[168:171], v64 offset:57344
	v_xor_b32_e32 v48, 0x80000000, v154
	v_mov_b32_e32 v49, v48
	v_mov_b32_e32 v50, v48
	v_mov_b32_e32 v51, v48
	v_mov_b32_e32 v52, v48
	v_mov_b32_e32 v53, v48
	v_mov_b32_e32 v54, v48
	v_mov_b32_e32 v55, v48
	v_mov_b32_e32 v56, v48
	v_mov_b32_e32 v57, v48
	v_mov_b32_e32 v58, v48
	v_mov_b32_e32 v59, v48
	v_mov_b32_e32 v60, v48
	v_mov_b32_e32 v61, v48
	v_mov_b32_e32 v62, v48
	v_mov_b32_e32 v63, v48
	v_add_u32_e32 v120, s4, v148
	v_exp_f32_e32 v162, v36
	s_waitcnt lgkmcnt(1)
	v_mfma_f32_32x32x16_bf16 v[64:79], v[158:161], v[92:95], v[48:63]
	v_exp_f32_e32 v163, v37
	v_exp_f32_e32 v172, v42
	v_exp_f32_e32 v173, v43
	v_exp_f32_e32 v174, v44
	v_exp_f32_e32 v175, v45
	v_exp_f32_e32 v176, v46
	v_exp_f32_e32 v177, v47
	s_waitcnt lgkmcnt(0)
	v_mfma_f32_32x32x16_bf16 v[48:63], v[168:171], v[92:95], v[48:63]
	ds_read_b128 v[158:161], v120 offset:49152
	ds_read_b128 v[168:171], v120 offset:57344
	v_add_u32_e32 v120, s4, v147
	s_waitcnt lgkmcnt(1)
	v_mfma_f32_32x32x16_bf16 v[64:79], v[158:161], v[88:91], v[64:79]
	s_waitcnt lgkmcnt(0)
	v_mfma_f32_32x32x16_bf16 v[48:63], v[168:171], v[88:91], v[48:63]
	ds_read_b128 v[158:161], v120 offset:49152
	ds_read_b128 v[168:171], v120 offset:57344
	v_add_u32_e32 v120, s4, v146
	s_waitcnt lgkmcnt(1)
	v_mfma_f32_32x32x16_bf16 v[64:79], v[158:161], v[84:87], v[64:79]
	s_waitcnt lgkmcnt(0)
	v_mfma_f32_32x32x16_bf16 v[48:63], v[168:171], v[84:87], v[48:63]
	ds_read_b128 v[158:161], v120 offset:49152
	ds_read_b128 v[168:171], v120 offset:57344
	v_add_u32_e32 v120, s4, v144
	s_waitcnt lgkmcnt(1)
	v_mfma_f32_32x32x16_bf16 v[64:79], v[158:161], v[80:83], v[64:79]
	s_waitcnt lgkmcnt(0)
	v_mfma_f32_32x32x16_bf16 v[48:63], v[168:171], v[80:83], v[48:63]
	ds_read_b128 v[158:161], v120 offset:49152
	ds_read_b128 v[168:171], v120 offset:57344
	v_add_u32_e32 v120, s4, v143
	s_waitcnt lgkmcnt(1)
	v_mfma_f32_32x32x16_bf16 v[64:79], v[158:161], v[96:99], v[64:79]
	s_waitcnt lgkmcnt(0)
	v_mfma_f32_32x32x16_bf16 v[48:63], v[168:171], v[96:99], v[48:63]
	ds_read_b128 v[158:161], v120 offset:49152
	ds_read_b128 v[168:171], v120 offset:57344
	s_waitcnt lgkmcnt(1)
	v_mfma_f32_32x32x16_bf16 v[64:79], v[158:161], v[100:103], v[64:79]
	v_exp_f32_e32 v158, v32
	v_exp_f32_e32 v159, v33
	v_exp_f32_e32 v160, v34
	v_exp_f32_e32 v161, v35
	v_pk_add_f32 v[32:33], v[136:137], v[134:135]
	v_pk_add_f32 v[34:35], v[160:161], v[158:159]
	s_waitcnt lgkmcnt(0)
	v_mfma_f32_32x32x16_bf16 v[48:63], v[168:171], v[100:103], v[48:63]
	v_exp_f32_e32 v168, v38
	v_exp_f32_e32 v169, v39
	v_exp_f32_e32 v170, v40
	v_exp_f32_e32 v171, v41
	v_pk_add_f32 v[32:33], v[132:133], v[32:33]
	v_pk_add_f32 v[34:35], v[162:163], v[34:35]
	v_pk_add_f32 v[32:33], v[130:131], v[32:33]
	v_pk_add_f32 v[34:35], v[168:169], v[34:35]
	v_pk_add_f32 v[32:33], v[128:129], v[32:33]
	v_pk_add_f32 v[34:35], v[170:171], v[34:35]
	v_pk_add_f32 v[32:33], v[126:127], v[32:33]
	v_pk_add_f32 v[34:35], v[172:173], v[34:35]
	v_pk_add_f32 v[32:33], v[124:125], v[32:33]
	v_pk_add_f32 v[34:35], v[174:175], v[34:35]
	v_pk_add_f32 v[32:33], v[122:123], v[32:33]
	v_pk_add_f32 v[34:35], v[176:177], v[34:35]
	s_nop 0
	v_pk_add_f32 v[32:33], v[32:33], v[34:35]
	s_nop 0
	v_pk_add_f32 v[120:121], v[32:33], v[32:33] op_sel:[0,1] op_sel_hi:[1,0]
	v_cvt_pk_bf16_f32 v32, v136, v137
	v_cvt_pk_bf16_f32 v33, v134, v135
	v_cvt_pk_bf16_f32 v34, v132, v133
	v_cvt_pk_bf16_f32 v35, v130, v131
	v_cvt_pk_bf16_f32 v36, v128, v129
	s_nop 0
	v_mov_b32_e32 v157, v120
	s_nop 1
	v_permlane32_swap_b32_e32 v120, v157
	v_permlane32_swap_b32_e32 v32, v34
	v_cvt_pk_bf16_f32 v37, v126, v127
	v_cvt_pk_bf16_f32 v38, v124, v125
	v_cvt_pk_bf16_f32 v39, v122, v123
	v_cvt_pk_bf16_f32 v40, v158, v159
	v_cvt_pk_bf16_f32 v41, v160, v161
	v_cvt_pk_bf16_f32 v42, v162, v163
	v_cvt_pk_bf16_f32 v43, v168, v169
	v_cvt_pk_bf16_f32 v44, v170, v171
	v_cvt_pk_bf16_f32 v45, v172, v173
	v_cvt_pk_bf16_f32 v46, v174, v175
	v_cvt_pk_bf16_f32 v47, v176, v177
	v_permlane32_swap_b32_e32 v33, v35
	v_permlane32_swap_b32_e32 v36, v38
	v_permlane32_swap_b32_e32 v37, v39
	v_permlane32_swap_b32_e32 v40, v42
	v_permlane32_swap_b32_e32 v41, v43
	v_permlane32_swap_b32_e32 v44, v46
	v_permlane32_swap_b32_e32 v45, v47
	v_add_u32_e32 v121, s90, v142
	ds_read_b64_tr_b16 v[122:123], v121 offset:0
	ds_read_b64_tr_b16 v[124:125], v121 offset:0x800
	ds_read_b64_tr_b16 v[126:127], v121 offset:0x1000
	ds_read_b64_tr_b16 v[128:129], v121 offset:0x1800
	ds_read_b64_tr_b16 v[130:131], v121 offset:0x2000
	ds_read_b64_tr_b16 v[132:133], v121 offset:0x2800
	ds_read_b64_tr_b16 v[134:135], v121 offset:0x3000
	ds_read_b64_tr_b16 v[136:137], v121 offset:0x3800
	s_waitcnt lgkmcnt(0)
	s_nop 0
	v_mfma_f32_32x32x16_bf16 v[0:15], v[32:35], v[122:125], v[0:15]
	ds_read_b64_tr_b16 v[122:123], v121 offset:0x200
	ds_read_b64_tr_b16 v[124:125], v121 offset:0xa00
	v_mfma_f32_32x32x16_bf16 v[0:15], v[36:39], v[126:129], v[0:15]
	ds_read_b64_tr_b16 v[126:127], v121 offset:0x1200
	ds_read_b64_tr_b16 v[128:129], v121 offset:0x1a00
	v_mfma_f32_32x32x16_bf16 v[0:15], v[40:43], v[130:133], v[0:15]
	ds_read_b64_tr_b16 v[130:131], v121 offset:0x2200
	ds_read_b64_tr_b16 v[132:133], v121 offset:0x2a00
	v_mfma_f32_32x32x16_bf16 v[0:15], v[44:47], v[134:137], v[0:15]
	ds_read_b64_tr_b16 v[134:135], v121 offset:0x3200
	ds_read_b64_tr_b16 v[136:137], v121 offset:0x3a00
	s_waitcnt lgkmcnt(0)
	v_add_u32_e32 v180, s78, v153
	s_add_i32 s14, s78, 0
	s_waitcnt vmcnt(1)
	ds_write_b128 v180, v[112:115]
	v_add_u32_e32 v180, s14, v151
	s_and_b64 vcc, exec, s[8:9]
	s_waitcnt vmcnt(0)
	ds_write_b128 v180, v[108:111] offset:49152
	s_cbranch_vccnz .Lmy_stage_1_a
	v_add_u32_e32 v180, s14, v152
	ds_write_b128 v180, v[104:107] offset:49152
; template <bool FIRST>
; __device__ __forceinline__ void partialSM(f32x16& p0, f32x16& p1, float& m_reg, float& alpha) {
;   float a = fmaxf(fmaxf(p0[0], p0[1]), p0[2]), b = fmaxf(fmaxf(p1[0], p1[1]), p1[2]);
; #pragma unroll
;   for (int r = 3; r < 15; r += 2) { a = fmaxf(fmaxf(a, p0[r]), p0[r + 1]); b = fmaxf(fmaxf(b, p1[r]), p1[r + 1]); }
;   float pmax = fmaxf(fmaxf(a, b), fmaxf(p0[15], p1[15]));
;   { auto rr = __builtin_amdgcn_permlane32_swap(__float_as_uint(pmax), __float_as_uint(pmax), false, false);
;     pmax = fmaxf(__uint_as_float(rr[0]), __uint_as_float(rr[1])); }
;   alpha = 1.f;
;   if (FIRST || !__builtin_expect(__all(pmax <= THRL), 1)) {
;     const float dl = FIRST ? pmax : fmaxf(pmax, 0.f);
;     m_reg += dl; if (!FIRST) alpha = __builtin_amdgcn_exp2f(-dl);
; #pragma unroll
;     for (int r = 0; r < 16; ++r) { p0[r] -= dl; p1[r] -= dl; }
;   }
; #pragma unroll
;   for (int r = 0; r < 16; ++r) p0[r] = __builtin_amdgcn_exp2f(p0[r]);
; }
; __device__ __forceinline__ void finishSM(f32x16& p0, f32x16& p1, float alpha, float& l_reg, bf16x8& pa0, bf16x8& pa1, bf16x8& pa2, bf16x8& pa3) {
; #pragma unroll
;   for (int r = 0; r < 16; ++r) p1[r] = __builtin_amdgcn_exp2f(p1[r]);
;   typedef float f2_t __attribute__((ext_vector_type(2)));
;   f2_t s2a = {p0[0], p0[1]}, s2b = {p1[0], p1[1]};
; #pragma unroll
;   for (int r = 2; r < 16; r += 2) { s2a += (f2_t){p0[r], p0[r + 1]}; s2b += (f2_t){p1[r], p1[r + 1]}; }
;   s2a += s2b; float ps = s2a.x + s2a.y;
;   { auto rr = __builtin_amdgcn_permlane32_swap(__float_as_uint(ps), __float_as_uint(ps), false, false);
;     ps = __uint_as_float(rr[0]) + __uint_as_float(rr[1]); }
;   l_reg = l_reg * alpha + ps;
;     ...
;   PK4(p0, 0, pa0); PK4(p0, 8, pa1); PK4(p1, 0, pa2); PK4(p1, 8, pa3);
;     ...
; }
; __device__ __forceinline__ void qkt(f32x16& p0, f32x16& p1, const char* Ks, const bf16x8* qr, int r32, int hi, float m_reg) {
; #pragma unroll
;   for (int r = 0; r < 16; ++r) { p0[r] = -m_reg; p1[r] = -m_reg; }
; #pragma unroll
;   for (int d0 = 0; d0 < 6; ++d0) { int cb = (d0 * 16 + hi * 8) * 2;
;     bf16x8 b0 = *reinterpret_cast<const bf16x8*>(Ks + KSWZ(r32, cb));
;     bf16x8 b1 = *reinterpret_cast<const bf16x8*>(Ks + KSWZ(32 + r32, cb));
;     p0 = __builtin_amdgcn_mfma_f32_32x32x16_bf16(b0, qr[d0], p0, 0, 0, 0);
;     p1 = __builtin_amdgcn_mfma_f32_32x32x16_bf16(b1, qr[d0], p1, 0, 0, 0); }
; }
.Lmy_stage_1_a:
	v_add_u32_e32 v180, 0xffff0000, v155
	v_add_u32_e32 v160, s79, v145
	v_add_u32_e32 v181, 0x48000, v160
	global_load_dwordx4 v[112:115], v180, s[10:11]
	global_load_dwordx4 v[108:111], v181, s[0:1]
	s_and_b64 vcc, exec, s[8:9]
	s_cbranch_vccnz .Lmy_stage_1_b
	v_add_u32_e32 v180, s79, v149
	v_add_u32_e32 v180, 0x48000, v180
	global_load_dwordx4 v[104:107], v180, s[0:1]
.Lmy_stage_1_b:
	v_mfma_f32_32x32x16_bf16 v[16:31], v[32:35], v[122:125], v[16:31]
	v_max3_f32 v32, v64, v65, v66
	v_max3_f32 v33, v48, v49, v50
	v_max3_f32 v32, v32, v67, v68
	v_max3_f32 v33, v33, v51, v52
	v_max3_f32 v32, v32, v69, v70
	v_max3_f32 v33, v33, v53, v54
	v_max3_f32 v32, v32, v71, v72
	v_mfma_f32_32x32x16_bf16 v[16:31], v[36:39], v[126:129], v[16:31]
	v_max3_f32 v33, v33, v55, v56
	v_max3_f32 v32, v32, v73, v74
	v_max3_f32 v33, v33, v57, v58
	v_max3_f32 v32, v32, v75, v76
	v_max3_f32 v33, v33, v59, v60
	v_max_f32_e32 v34, v63, v63
	v_max_f32_e32 v35, v79, v79
	v_mfma_f32_32x32x16_bf16 v[16:31], v[40:43], v[130:133], v[16:31]
	v_max3_f32 v32, v32, v77, v78
	v_max3_f32 v33, v33, v61, v62
	v_max_f32_e32 v34, v35, v34
	v_max3_f32 v32, v32, v33, v34
	v_mov_b32_e32 v33, v32
	s_nop 1
	v_permlane32_swap_b32_e32 v32, v33
	v_mfma_f32_32x32x16_bf16 v[16:31], v[44:47], v[134:137], v[16:31]
	v_max_f32_e32 v33, v33, v33
	v_max_f32_e32 v32, v32, v32
	v_max_f32_e32 v32, v32, v33
	v_cmp_ge_f32_e32 vcc, s75, v32
	s_cmp_eq_u64 vcc, exec
	s_cbranch_scc0 .LBB0_689
	v_mov_b32_e32 v159, 1.0
.LBB0_669:
.LBB0_673:
	v_cmp_gt_f32_e32 vcc, 1.0, v159
	s_cbranch_vccz .LBB0_677
	s_and_saveexec_b64 s[4:5], s[6:7]
	ds_write_b32 v140, v159 offset:128
	s_or_b64 exec, exec, s[4:5]
	s_waitcnt lgkmcnt(0)
	v_add_u32_e32 v44, v119, v116
	ds_read_b128 v[32:35], v44 offset:224
	ds_read_b128 v[36:39], v44 offset:192
	ds_read_b128 v[40:43], v44 offset:160
	ds_read_b128 v[44:47], v44 offset:128
	s_waitcnt lgkmcnt(3)
	v_pk_mul_f32 v[12:13], v[12:13], v[32:33]
	s_waitcnt lgkmcnt(2)
	v_pk_mul_f32 v[8:9], v[8:9], v[36:37]
	s_waitcnt lgkmcnt(1)
	v_pk_mul_f32 v[4:5], v[4:5], v[40:41]
	v_pk_mul_f32 v[14:15], v[14:15], v[34:35]
	v_pk_mul_f32 v[10:11], v[10:11], v[38:39]
	v_pk_mul_f32 v[6:7], v[6:7], v[42:43]
	s_waitcnt lgkmcnt(0)
	v_pk_mul_f32 v[2:3], v[2:3], v[46:47]
	v_pk_mul_f32 v[0:1], v[0:1], v[44:45]
	v_pk_mul_f32 v[28:29], v[28:29], v[32:33]
	v_pk_mul_f32 v[24:25], v[24:25], v[36:37]
	v_pk_mul_f32 v[20:21], v[20:21], v[40:41]
	v_pk_mul_f32 v[30:31], v[30:31], v[34:35]
	v_pk_mul_f32 v[26:27], v[26:27], v[38:39]
	v_pk_mul_f32 v[22:23], v[22:23], v[42:43]
	v_pk_mul_f32 v[18:19], v[18:19], v[46:47]
	v_pk_mul_f32 v[16:17], v[16:17], v[44:45]
.LBB0_677:
	v_exp_f32_e32 v124, v64
	v_exp_f32_e32 v125, v65
	v_exp_f32_e32 v128, v66
	v_exp_f32_e32 v129, v67
	v_exp_f32_e32 v132, v68
	v_exp_f32_e32 v133, v69
	v_exp_f32_e32 v136, v70
	v_exp_f32_e32 v137, v71
	v_exp_f32_e32 v122, v72
	v_exp_f32_e32 v123, v73
	v_exp_f32_e32 v126, v74
	v_exp_f32_e32 v127, v75
	v_exp_f32_e32 v130, v76
	v_exp_f32_e32 v131, v77
	v_exp_f32_e32 v134, v78
	v_exp_f32_e32 v135, v79
	s_waitcnt lgkmcnt(0)
	s_barrier
	v_add_u32_e32 v64, s14, v150
	ds_read_b128 v[168:171], v64 offset:49152
	ds_read_b128 v[172:175], v64 offset:57344
	v_xor_b32_e32 v32, 0x80000000, v154
	v_mov_b32_e32 v33, v32
	v_mov_b32_e32 v34, v32
	v_mov_b32_e32 v35, v32
	v_mov_b32_e32 v36, v32
	v_mov_b32_e32 v37, v32
	v_mov_b32_e32 v38, v32
	v_mov_b32_e32 v39, v32
	v_mov_b32_e32 v40, v32
	v_mov_b32_e32 v41, v32
	v_mov_b32_e32 v42, v32
	v_mov_b32_e32 v43, v32
	v_mov_b32_e32 v44, v32
	v_mov_b32_e32 v45, v32
	v_mov_b32_e32 v46, v32
	v_mov_b32_e32 v47, v32
	v_add_u32_e32 v158, s14, v148
	v_exp_f32_e32 v162, v48
	s_waitcnt lgkmcnt(1)
	v_mfma_f32_32x32x16_bf16 v[64:79], v[168:171], v[92:95], v[32:47]
	v_exp_f32_e32 v163, v49
	v_exp_f32_e32 v176, v58
	v_exp_f32_e32 v177, v59
	v_pk_add_f32 v[48:49], v[128:129], v[124:125]
	v_exp_f32_e32 v178, v60
	v_exp_f32_e32 v179, v61
	v_pk_add_f32 v[48:49], v[132:133], v[48:49]
	s_waitcnt lgkmcnt(0)
	v_mfma_f32_32x32x16_bf16 v[32:47], v[172:175], v[92:95], v[32:47]
	ds_read_b128 v[168:171], v158 offset:49152
	ds_read_b128 v[172:175], v158 offset:57344
	v_add_u32_e32 v158, s14, v147
	v_exp_f32_e32 v62, v62
	v_exp_f32_e32 v63, v63
	v_pk_add_f32 v[48:49], v[136:137], v[48:49]
	s_nop 0
	v_pk_add_f32 v[48:49], v[122:123], v[48:49]
	s_waitcnt lgkmcnt(1)
	v_mfma_f32_32x32x16_bf16 v[64:79], v[168:171], v[88:91], v[64:79]
	v_add_f32_e64 v48, v126, v48
	v_add_f32_e64 v49, v127, v49
	v_add_f32_e64 v48, v130, v48
	v_add_f32_e64 v49, v131, v49
	v_add_f32_e64 v48, v134, v48
	v_add_f32_e64 v49, v135, v49
	s_waitcnt lgkmcnt(0)
	v_mfma_f32_32x32x16_bf16 v[32:47], v[172:175], v[88:91], v[32:47]
	ds_read_b128 v[168:171], v158 offset:49152
	ds_read_b128 v[172:175], v158 offset:57344
	v_add_u32_e32 v158, s14, v146
	s_waitcnt lgkmcnt(1)
	v_mfma_f32_32x32x16_bf16 v[64:79], v[168:171], v[84:87], v[64:79]
	s_waitcnt lgkmcnt(0)
	v_mfma_f32_32x32x16_bf16 v[32:47], v[172:175], v[84:87], v[32:47]
	ds_read_b128 v[168:171], v158 offset:49152
	ds_read_b128 v[172:175], v158 offset:57344
	v_add_u32_e32 v158, s14, v144
	s_waitcnt lgkmcnt(1)
	v_mfma_f32_32x32x16_bf16 v[64:79], v[168:171], v[80:83], v[64:79]
	s_waitcnt lgkmcnt(0)
	v_mfma_f32_32x32x16_bf16 v[32:47], v[172:175], v[80:83], v[32:47]
	ds_read_b128 v[168:171], v158 offset:49152
	ds_read_b128 v[172:175], v158 offset:57344
	v_add_u32_e32 v158, s14, v143
	s_waitcnt lgkmcnt(1)
	v_mfma_f32_32x32x16_bf16 v[64:79], v[168:171], v[96:99], v[64:79]
	s_waitcnt lgkmcnt(0)
	v_mfma_f32_32x32x16_bf16 v[32:47], v[172:175], v[96:99], v[32:47]
	ds_read_b128 v[168:171], v158 offset:49152
	ds_read_b128 v[172:175], v158 offset:57344
	s_waitcnt lgkmcnt(1)
; __device__ __forceinline__ void finishSM(f32x16& p0, f32x16& p1, float alpha, float& l_reg, bf16x8& pa0, bf16x8& pa1, bf16x8& pa2, bf16x8& pa3) {
; #pragma unroll
;   for (int r = 0; r < 16; ++r) p1[r] = __builtin_amdgcn_exp2f(p1[r]);
;   typedef float f2_t __attribute__((ext_vector_type(2)));
;   f2_t s2a = {p0[0], p0[1]}, s2b = {p1[0], p1[1]};
; #pragma unroll
;   for (int r = 2; r < 16; r += 2) { s2a += (f2_t){p0[r], p0[r + 1]}; s2b += (f2_t){p1[r], p1[r + 1]}; }
;   s2a += s2b; float ps = s2a.x + s2a.y;
;   { auto rr = __builtin_amdgcn_permlane32_swap(__float_as_uint(ps), __float_as_uint(ps), false, false);
;     ps = __uint_as_float(rr[0]) + __uint_as_float(rr[1]); }
;   l_reg = l_reg * alpha + ps;
;     ...
;   PK4(p0, 0, pa0); PK4(p0, 8, pa1); PK4(p1, 0, pa2); PK4(p1, 8, pa3);
;     ...
; }
; __device__ __forceinline__ void qkt(f32x16& p0, f32x16& p1, const char* Ks, const bf16x8* qr, int r32, int hi, float m_reg) {
; #pragma unroll
;   for (int r = 0; r < 16; ++r) { p0[r] = -m_reg; p1[r] = -m_reg; }
; #pragma unroll
;   for (int d0 = 0; d0 < 6; ++d0) { int cb = (d0 * 16 + hi * 8) * 2;
;     bf16x8 b0 = *reinterpret_cast<const bf16x8*>(Ks + KSWZ(r32, cb));
;     bf16x8 b1 = *reinterpret_cast<const bf16x8*>(Ks + KSWZ(32 + r32, cb));
;     p0 = __builtin_amdgcn_mfma_f32_32x32x16_bf16(b0, qr[d0], p0, 0, 0, 0);
;     p1 = __builtin_amdgcn_mfma_f32_32x32x16_bf16(b1, qr[d0], p1, 0, 0, 0); }
; }
; __device__ __forceinline__ int v_st(int k, int c) { const int kk = (k & ~0xC) | ((k & 4) << 1) | ((k & 8) >> 1); return ((kk >> 3) * 4 + (c >> 5)) * 512 + ((kk & 7) * 32 + (c & 31)) * 2; }
; __device__ __forceinline__ int v_rd_base(int lane) { return ((lane & 3) << 3) | (((lane >> 2) & 3) << 6) | (((lane >> 4) & 1) << 5) | (((lane >> 5) & 1) << 8); }
; template <int OFF> __device__ __forceinline__ s16x4 tr_read(int vb) {
;   s16x4 r; asm volatile("ds_read_b64_tr_b16 %0, %1 offset:%2" : "=&v"(r) : "v"(vb), "i"(OFF) : "memory"); return r;
; }
; template <int D0> __device__ __forceinline__ void pv_one(f32x16& od, int vb, bf16x8 pa0, bf16x8 pa1, bf16x8 pa2, bf16x8 pa3) {
;   const s16x4 l0 = tr_read<v_rd_off(D0, 0, 0)>(vb), h0 = tr_read<v_rd_off(D0, 0, 1)>(vb), l1 = tr_read<v_rd_off(D0, 1, 0)>(vb), h1 = tr_read<v_rd_off(D0, 1, 1)>(vb);
	v_mfma_f32_32x32x16_bf16 v[64:79], v[168:171], v[100:103], v[64:79]
	v_exp_f32_e32 v168, v50
	v_exp_f32_e32 v169, v51
	v_exp_f32_e32 v170, v52
	v_exp_f32_e32 v171, v53
	v_pk_add_f32 v[50:51], v[162:163], v[168:169]
	s_nop 0
	v_pk_add_f32 v[50:51], v[170:171], v[50:51]
	s_waitcnt lgkmcnt(0)
	v_mfma_f32_32x32x16_bf16 v[32:47], v[172:175], v[100:103], v[32:47]
	v_exp_f32_e32 v172, v54
	v_exp_f32_e32 v173, v55
	v_exp_f32_e32 v174, v56
	v_exp_f32_e32 v175, v57
	v_pk_add_f32 v[50:51], v[172:173], v[50:51]
	s_nop 0
	v_pk_add_f32 v[50:51], v[174:175], v[50:51]
	s_nop 0
	v_pk_add_f32 v[50:51], v[176:177], v[50:51]
	s_nop 0
	v_pk_add_f32 v[50:51], v[178:179], v[50:51]
	s_nop 0
	v_pk_add_f32 v[50:51], v[62:63], v[50:51]
	s_nop 0
	v_pk_add_f32 v[48:49], v[48:49], v[50:51]
	v_cvt_pk_bf16_f32 v50, v124, v125
	v_cvt_pk_bf16_f32 v51, v128, v129
	v_cvt_pk_bf16_f32 v52, v132, v133
	v_cvt_pk_bf16_f32 v53, v136, v137
	v_cvt_pk_bf16_f32 v54, v122, v123
	s_nop 0
	v_pk_add_f32 v[48:49], v[48:49], v[48:49] op_sel:[0,1] op_sel_hi:[1,0]
	v_permlane32_swap_b32_e32 v50, v52
	v_mov_b32_e32 v49, v48
	s_nop 1
	v_permlane32_swap_b32_e32 v48, v49
	v_cvt_pk_bf16_f32 v55, v126, v127
	v_cvt_pk_bf16_f32 v56, v130, v131
	v_cvt_pk_bf16_f32 v57, v134, v135
	v_cvt_pk_bf16_f32 v58, v162, v163
	v_cvt_pk_bf16_f32 v59, v168, v169
	v_cvt_pk_bf16_f32 v60, v170, v171
	v_cvt_pk_bf16_f32 v61, v172, v173
	v_cvt_pk_bf16_f32 v122, v174, v175
	v_cvt_pk_bf16_f32 v123, v176, v177
	v_cvt_pk_bf16_f32 v124, v178, v179
	v_cvt_pk_bf16_f32 v125, v62, v63
	v_permlane32_swap_b32_e32 v51, v53
	v_permlane32_swap_b32_e32 v54, v56
	v_permlane32_swap_b32_e32 v55, v57
	v_permlane32_swap_b32_e32 v58, v60
	v_permlane32_swap_b32_e32 v59, v61
	v_permlane32_swap_b32_e32 v122, v124
	v_permlane32_swap_b32_e32 v123, v125
	v_add_u32_e32 v62, s24, v142
	ds_read_b64_tr_b16 v[126:127], v62 offset:0
	ds_read_b64_tr_b16 v[128:129], v62 offset:0x800
	ds_read_b64_tr_b16 v[130:131], v62 offset:0x1000
	ds_read_b64_tr_b16 v[132:133], v62 offset:0x1800
	ds_read_b64_tr_b16 v[134:135], v62 offset:0x2000
	ds_read_b64_tr_b16 v[136:137], v62 offset:0x2800
	ds_read_b64_tr_b16 v[168:169], v62 offset:0x3000
	ds_read_b64_tr_b16 v[170:171], v62 offset:0x3800
	s_waitcnt lgkmcnt(0)
	s_nop 0
	v_mfma_f32_32x32x16_bf16 v[0:15], v[50:53], v[126:129], v[0:15]
	ds_read_b64_tr_b16 v[126:127], v62 offset:0x200
	ds_read_b64_tr_b16 v[128:129], v62 offset:0xa00
	v_mfma_f32_32x32x16_bf16 v[0:15], v[54:57], v[130:133], v[0:15]
	ds_read_b64_tr_b16 v[130:131], v62 offset:0x1200
	ds_read_b64_tr_b16 v[132:133], v62 offset:0x1a00
	v_mfma_f32_32x32x16_bf16 v[0:15], v[58:61], v[134:137], v[0:15]
	ds_read_b64_tr_b16 v[134:135], v62 offset:0x2200
	ds_read_b64_tr_b16 v[136:137], v62 offset:0x2a00
	v_mfma_f32_32x32x16_bf16 v[0:15], v[122:125], v[168:171], v[0:15]
	ds_read_b64_tr_b16 v[168:169], v62 offset:0x3200
	ds_read_b64_tr_b16 v[170:171], v62 offset:0x3a00
	s_waitcnt lgkmcnt(0)
	v_add_u32_e32 v180, s90, v153
	s_add_i32 s25, s90, 0
	s_waitcnt vmcnt(1)
	ds_write_b128 v180, v[112:115]
	v_add_u32_e32 v180, s25, v151
	s_and_b64 vcc, exec, s[8:9]
	s_waitcnt vmcnt(0)
	ds_write_b128 v180, v[108:111] offset:49152
	s_cbranch_vccnz .Lmy_stage_0_a
	v_add_u32_e32 v180, s25, v152
	ds_write_b128 v180, v[104:107] offset:49152
.Lmy_stage_0_a:
	s_cmpk_gt_u32 s87, 0xfc
	s_cselect_b64 s[4:5], -1, 0
	s_and_b64 vcc, exec, s[4:5]
	s_cbranch_vccnz .Lmy_stage_0_b
	v_add_u32_e32 v180, 0x60000, v160
	global_load_dwordx4 v[112:115], v155, s[10:11]
	global_load_dwordx4 v[108:111], v180, s[0:1]
	s_and_b64 vcc, exec, s[8:9]
	s_cbranch_vccnz .Lmy_stage_0_b
	v_add_u32_e32 v180, s79, v149
	v_add_u32_e32 v180, 0x60000, v180
	global_load_dwordx4 v[104:107], v180, s[0:1]
.Lmy_stage_0_b:
	v_mfma_f32_32x32x16_bf16 v[16:31], v[50:53], v[126:129], v[16:31]
	v_max3_f32 v50, v64, v65, v66
	v_max3_f32 v51, v32, v33, v34
	v_max3_f32 v50, v50, v67, v68
	v_max3_f32 v51, v51, v35, v36
	v_max3_f32 v50, v50, v69, v70
	v_max3_f32 v51, v51, v37, v38
	v_max3_f32 v50, v50, v71, v72
	v_mfma_f32_32x32x16_bf16 v[16:31], v[54:57], v[130:133], v[16:31]
	v_max3_f32 v51, v51, v39, v40
	v_max3_f32 v50, v50, v73, v74
	v_max3_f32 v51, v51, v41, v42
	v_max3_f32 v50, v50, v75, v76
	v_max3_f32 v51, v51, v43, v44
	v_max_f32_e32 v52, v47, v47
	v_max_f32_e32 v53, v79, v79
	v_mfma_f32_32x32x16_bf16 v[16:31], v[58:61], v[134:137], v[16:31]
	v_max3_f32 v50, v50, v77, v78
	v_max3_f32 v51, v51, v45, v46
	v_max_f32_e32 v52, v53, v52
	v_max3_f32 v50, v50, v51, v52
	v_mov_b32_e32 v51, v50
	s_nop 1
	v_permlane32_swap_b32_e32 v50, v51
	v_mfma_f32_32x32x16_bf16 v[16:31], v[122:125], v[168:171], v[16:31]
	v_max_f32_e32 v51, v51, v51
	v_max_f32_e32 v50, v50, v50
	v_max_f32_e32 v50, v50, v51
	v_cmp_ge_f32_e32 vcc, s75, v50
	s_cmp_eq_u64 vcc, exec
	v_mov_b32_e32 v158, 1.0
	s_cbranch_scc0 .LBB0_690
.LBB0_678:
.LBB0_683:
	v_cmp_gt_f32_e32 vcc, 1.0, v158
	s_cbranch_vccz .LBB0_687
	s_and_saveexec_b64 s[14:15], s[6:7]
	ds_write_b32 v140, v158 offset:128
	s_or_b64 exec, exec, s[14:15]
	s_waitcnt lgkmcnt(0)
	v_add_u32_e32 v62, v119, v116
	ds_read_b128 v[50:53], v62 offset:224
	ds_read_b128 v[54:57], v62 offset:192
	ds_read_b128 v[58:61], v62 offset:160
	ds_read_b128 v[122:125], v62 offset:128
	s_waitcnt lgkmcnt(3)
	v_pk_mul_f32 v[12:13], v[12:13], v[50:51]
	s_waitcnt lgkmcnt(2)
	v_pk_mul_f32 v[8:9], v[8:9], v[54:55]
	s_waitcnt lgkmcnt(1)
	v_pk_mul_f32 v[4:5], v[4:5], v[58:59]
	v_pk_mul_f32 v[14:15], v[14:15], v[52:53]
	v_pk_mul_f32 v[10:11], v[10:11], v[56:57]
	v_pk_mul_f32 v[6:7], v[6:7], v[60:61]
	s_waitcnt lgkmcnt(0)
	v_pk_mul_f32 v[2:3], v[2:3], v[124:125]
	v_pk_mul_f32 v[0:1], v[0:1], v[122:123]
	v_pk_mul_f32 v[28:29], v[28:29], v[50:51]
	v_pk_mul_f32 v[24:25], v[24:25], v[54:55]
	v_pk_mul_f32 v[20:21], v[20:21], v[58:59]
	v_pk_mul_f32 v[30:31], v[30:31], v[52:53]
	v_pk_mul_f32 v[26:27], v[26:27], v[56:57]
	v_pk_mul_f32 v[22:23], v[22:23], v[60:61]
	v_pk_mul_f32 v[18:19], v[18:19], v[124:125]
	v_pk_mul_f32 v[16:17], v[16:17], v[122:123]

; __device__ __forceinline__ void finishSM(f32x16& p0, f32x16& p1, float alpha, float& l_reg, bf16x8& pa0, bf16x8& pa1, bf16x8& pa2, bf16x8& pa3) {
; #pragma unroll
;   for (int r = 0; r < 16; ++r) p1[r] = __builtin_amdgcn_exp2f(p1[r]);
;   typedef float f2_t __attribute__((ext_vector_type(2)));
;   f2_t s2a = {p0[0], p0[1]}, s2b = {p1[0], p1[1]};
; #pragma unroll
;   for (int r = 2; r < 16; r += 2) { s2a += (f2_t){p0[r], p0[r + 1]}; s2b += (f2_t){p1[r], p1[r + 1]}; }
;   s2a += s2b; float ps = s2a.x + s2a.y;
;   { auto rr = __builtin_amdgcn_permlane32_swap(__float_as_uint(ps), __float_as_uint(ps), false, false);
;     ps = __uint_as_float(rr[0]) + __uint_as_float(rr[1]); }
;   l_reg = l_reg * alpha + ps;
;     ...
;   PK4(p0, 0, pa0); PK4(p0, 8, pa1); PK4(p1, 0, pa2); PK4(p1, 8, pa3);
;     ...
; }
; __device__ __forceinline__ void qkt(f32x16& p0, f32x16& p1, const char* Ks, const bf16x8* qr, int r32, int hi, float m_reg) {
; #pragma unroll
;   for (int r = 0; r < 16; ++r) { p0[r] = -m_reg; p1[r] = -m_reg; }
; #pragma unroll
;   for (int d0 = 0; d0 < 6; ++d0) { int cb = (d0 * 16 + hi * 8) * 2;
;     bf16x8 b0 = *reinterpret_cast<const bf16x8*>(Ks + KSWZ(r32, cb));
;     bf16x8 b1 = *reinterpret_cast<const bf16x8*>(Ks + KSWZ(32 + r32, cb));
;     p0 = __builtin_amdgcn_mfma_f32_32x32x16_bf16(b0, qr[d0], p0, 0, 0, 0);
;     p1 = __builtin_amdgcn_mfma_f32_32x32x16_bf16(b1, qr[d0], p1, 0, 0, 0); }
; }
; __device__ __forceinline__ int v_st(int k, int c) { const int kk = (k & ~0xC) | ((k & 4) << 1) | ((k & 8) >> 1); return ((kk >> 3) * 4 + (c >> 5)) * 512 + ((kk & 7) * 32 + (c & 31)) * 2; }
; __device__ __forceinline__ int v_rd_base(int lane) { return ((lane & 3) << 3) | (((lane >> 2) & 3) << 6) | (((lane >> 4) & 1) << 5) | (((lane >> 5) & 1) << 8); }
; template <int OFF> __device__ __forceinline__ s16x4 tr_read(int vb) {
;   s16x4 r; asm volatile("ds_read_b64_tr_b16 %0, %1 offset:%2" : "=&v"(r) : "v"(vb), "i"(OFF) : "memory"); return r;
; }
; template <int D0> __device__ __forceinline__ void pv_one(f32x16& od, int vb, bf16x8 pa0, bf16x8 pa1, bf16x8 pa2, bf16x8 pa3) {
;   const s16x4 l0 = tr_read<v_rd_off(D0, 0, 0)>(vb), h0 = tr_read<v_rd_off(D0, 0, 1)>(vb), l1 = tr_read<v_rd_off(D0, 1, 0)>(vb), h1 = tr_read<v_rd_off(D0, 1, 1)>(vb);
.LBB0_714:
	s_mov_b32 s24, s87
	s_mov_b32 s87, s4
	s_add_i32 s4, s24, 0
	v_add_u32_e32 v64, s4, v150
	ds_read_b128 v[158:161], v64 offset:49152
	ds_read_b128 v[168:171], v64 offset:57344
	v_xor_b32_e32 v48, 0x80000000, v154
	v_mov_b32_e32 v49, v48
	v_mov_b32_e32 v50, v48
	v_mov_b32_e32 v51, v48
	v_mov_b32_e32 v52, v48
	v_mov_b32_e32 v53, v48
	v_mov_b32_e32 v54, v48
	v_mov_b32_e32 v55, v48
	v_mov_b32_e32 v56, v48
	v_mov_b32_e32 v57, v48
	v_mov_b32_e32 v58, v48
	v_mov_b32_e32 v59, v48
	v_mov_b32_e32 v60, v48
	v_mov_b32_e32 v61, v48
	v_mov_b32_e32 v62, v48
	v_mov_b32_e32 v63, v48
	v_add_u32_e32 v120, s4, v148
	v_exp_f32_e32 v162, v36
	s_waitcnt lgkmcnt(1)
	v_mfma_f32_32x32x16_bf16 v[64:79], v[158:161], v[92:95], v[48:63]
	v_exp_f32_e32 v163, v37
	v_exp_f32_e32 v172, v42
	v_exp_f32_e32 v173, v43
	v_exp_f32_e32 v174, v44
	v_exp_f32_e32 v175, v45
	v_exp_f32_e32 v176, v46
	v_exp_f32_e32 v177, v47
	s_waitcnt lgkmcnt(0)
	v_mfma_f32_32x32x16_bf16 v[48:63], v[168:171], v[92:95], v[48:63]
	ds_read_b128 v[158:161], v120 offset:49152
	ds_read_b128 v[168:171], v120 offset:57344
	v_add_u32_e32 v120, s4, v147
	s_waitcnt lgkmcnt(1)
	v_mfma_f32_32x32x16_bf16 v[64:79], v[158:161], v[88:91], v[64:79]
	s_waitcnt lgkmcnt(0)
	v_mfma_f32_32x32x16_bf16 v[48:63], v[168:171], v[88:91], v[48:63]
	ds_read_b128 v[158:161], v120 offset:49152
	ds_read_b128 v[168:171], v120 offset:57344
	v_add_u32_e32 v120, s4, v146
	s_waitcnt lgkmcnt(1)
	v_mfma_f32_32x32x16_bf16 v[64:79], v[158:161], v[84:87], v[64:79]
	s_waitcnt lgkmcnt(0)
	v_mfma_f32_32x32x16_bf16 v[48:63], v[168:171], v[84:87], v[48:63]
	ds_read_b128 v[158:161], v120 offset:49152
	ds_read_b128 v[168:171], v120 offset:57344
	v_add_u32_e32 v120, s4, v144
	s_waitcnt lgkmcnt(1)
	v_mfma_f32_32x32x16_bf16 v[64:79], v[158:161], v[80:83], v[64:79]
	s_waitcnt lgkmcnt(0)
	v_mfma_f32_32x32x16_bf16 v[48:63], v[168:171], v[80:83], v[48:63]
	ds_read_b128 v[158:161], v120 offset:49152
	ds_read_b128 v[168:171], v120 offset:57344
	v_add_u32_e32 v120, s4, v143
	s_waitcnt lgkmcnt(1)
	v_mfma_f32_32x32x16_bf16 v[64:79], v[158:161], v[96:99], v[64:79]
	s_waitcnt lgkmcnt(0)
	v_mfma_f32_32x32x16_bf16 v[48:63], v[168:171], v[96:99], v[48:63]
	ds_read_b128 v[158:161], v120 offset:49152
	ds_read_b128 v[168:171], v120 offset:57344
	s_waitcnt lgkmcnt(1)
	v_mfma_f32_32x32x16_bf16 v[64:79], v[158:161], v[100:103], v[64:79]
	v_exp_f32_e32 v158, v32
	v_exp_f32_e32 v159, v33
	v_exp_f32_e32 v160, v34
	v_exp_f32_e32 v161, v35
	v_pk_add_f32 v[32:33], v[136:137], v[134:135]
	v_pk_add_f32 v[34:35], v[160:161], v[158:159]
	s_waitcnt lgkmcnt(0)
	v_mfma_f32_32x32x16_bf16 v[48:63], v[168:171], v[100:103], v[48:63]
	v_exp_f32_e32 v168, v38
	v_exp_f32_e32 v169, v39
	v_exp_f32_e32 v170, v40
	v_exp_f32_e32 v171, v41
	v_pk_add_f32 v[32:33], v[132:133], v[32:33]
	v_pk_add_f32 v[34:35], v[162:163], v[34:35]
	v_pk_add_f32 v[32:33], v[130:131], v[32:33]
	v_pk_add_f32 v[34:35], v[168:169], v[34:35]
	v_pk_add_f32 v[32:33], v[128:129], v[32:33]
	v_pk_add_f32 v[34:35], v[170:171], v[34:35]
	v_pk_add_f32 v[32:33], v[126:127], v[32:33]
	v_pk_add_f32 v[34:35], v[172:173], v[34:35]
	v_pk_add_f32 v[32:33], v[124:125], v[32:33]
	v_pk_add_f32 v[34:35], v[174:175], v[34:35]
	v_pk_add_f32 v[32:33], v[122:123], v[32:33]
	v_pk_add_f32 v[34:35], v[176:177], v[34:35]
	s_nop 0
	v_pk_add_f32 v[32:33], v[32:33], v[34:35]
	s_nop 0
	v_pk_add_f32 v[120:121], v[32:33], v[32:33] op_sel:[0,1] op_sel_hi:[1,0]
	v_cvt_pk_bf16_f32 v32, v136, v137
	v_cvt_pk_bf16_f32 v33, v134, v135
	v_cvt_pk_bf16_f32 v34, v132, v133
	v_cvt_pk_bf16_f32 v35, v130, v131
	v_cvt_pk_bf16_f32 v36, v128, v129
	s_nop 0
	v_mov_b32_e32 v157, v120
	s_nop 1
	v_permlane32_swap_b32_e32 v120, v157
	v_permlane32_swap_b32_e32 v32, v34
	v_cvt_pk_bf16_f32 v37, v126, v127
	v_cvt_pk_bf16_f32 v38, v124, v125
	v_cvt_pk_bf16_f32 v39, v122, v123
	v_cvt_pk_bf16_f32 v40, v158, v159
	v_cvt_pk_bf16_f32 v41, v160, v161
	v_cvt_pk_bf16_f32 v42, v162, v163
	v_cvt_pk_bf16_f32 v43, v168, v169
	v_cvt_pk_bf16_f32 v44, v170, v171
	v_cvt_pk_bf16_f32 v45, v172, v173
	v_cvt_pk_bf16_f32 v46, v174, v175
	v_cvt_pk_bf16_f32 v47, v176, v177
	v_permlane32_swap_b32_e32 v33, v35
	v_permlane32_swap_b32_e32 v36, v38
	v_permlane32_swap_b32_e32 v37, v39
	v_permlane32_swap_b32_e32 v40, v42
	v_permlane32_swap_b32_e32 v41, v43
	v_permlane32_swap_b32_e32 v44, v46
	v_permlane32_swap_b32_e32 v45, v47
	v_add_u32_e32 v121, s87, v142
	ds_read_b64_tr_b16 v[122:123], v121 offset:0
	ds_read_b64_tr_b16 v[124:125], v121 offset:0x800
	ds_read_b64_tr_b16 v[126:127], v121 offset:0x1000
	ds_read_b64_tr_b16 v[128:129], v121 offset:0x1800
	ds_read_b64_tr_b16 v[130:131], v121 offset:0x2000
	ds_read_b64_tr_b16 v[132:133], v121 offset:0x2800
	ds_read_b64_tr_b16 v[134:135], v121 offset:0x3000
	ds_read_b64_tr_b16 v[136:137], v121 offset:0x3800
	s_waitcnt lgkmcnt(0)
	s_nop 0
	v_mfma_f32_32x32x16_bf16 v[0:15], v[32:35], v[122:125], v[0:15]
	ds_read_b64_tr_b16 v[122:123], v121 offset:0x200
	ds_read_b64_tr_b16 v[124:125], v121 offset:0xa00
	v_mfma_f32_32x32x16_bf16 v[0:15], v[36:39], v[126:129], v[0:15]
	ds_read_b64_tr_b16 v[126:127], v121 offset:0x1200
	ds_read_b64_tr_b16 v[128:129], v121 offset:0x1a00
	v_mfma_f32_32x32x16_bf16 v[0:15], v[40:43], v[130:133], v[0:15]
	ds_read_b64_tr_b16 v[130:131], v121 offset:0x2200
	ds_read_b64_tr_b16 v[132:133], v121 offset:0x2a00
	v_mfma_f32_32x32x16_bf16 v[0:15], v[44:47], v[134:137], v[0:15]
	ds_read_b64_tr_b16 v[134:135], v121 offset:0x3200
	ds_read_b64_tr_b16 v[136:137], v121 offset:0x3a00
	s_waitcnt lgkmcnt(0)
	v_add_u32_e32 v180, s89, v153
	s_add_i32 s14, s89, 0
	s_waitcnt vmcnt(1)
	ds_write_b128 v180, v[112:115]
	v_add_u32_e32 v180, s14, v151
	s_and_b64 vcc, exec, s[8:9]
	s_waitcnt vmcnt(0)
	ds_write_b128 v180, v[108:111] offset:49152
	s_cbranch_vccnz .Lmy_stage_3_a
	v_add_u32_e32 v180, s14, v152
	ds_write_b128 v180, v[104:107] offset:49152
; template <bool FIRST>
; __device__ __forceinline__ void partialSM(f32x16& p0, f32x16& p1, float& m_reg, float& alpha) {
;   float a = fmaxf(fmaxf(p0[0], p0[1]), p0[2]), b = fmaxf(fmaxf(p1[0], p1[1]), p1[2]);
; #pragma unroll
;   for (int r = 3; r < 15; r += 2) { a = fmaxf(fmaxf(a, p0[r]), p0[r + 1]); b = fmaxf(fmaxf(b, p1[r]), p1[r + 1]); }
;   float pmax = fmaxf(fmaxf(a, b), fmaxf(p0[15], p1[15]));
;   { auto rr = __builtin_amdgcn_permlane32_swap(__float_as_uint(pmax), __float_as_uint(pmax), false, false);
;     pmax = fmaxf(__uint_as_float(rr[0]), __uint_as_float(rr[1])); }
;   alpha = 1.f;
;   if (FIRST || !__builtin_expect(__all(pmax <= THRL), 1)) {
.Lmy_stage_3_a:
	v_add_u32_e32 v180, 0xffff0000, v155
	v_add_u32_e32 v160, s80, v145
	v_add_u32_e32 v181, 0x48000, v160
	global_load_dwordx4 v[112:115], v180, s[12:13]
	global_load_dwordx4 v[108:111], v181, s[10:11]
	s_and_b64 vcc, exec, s[8:9]
	s_cbranch_vccnz .Lmy_stage_3_b
	v_add_u32_e32 v180, s80, v149
	v_add_u32_e32 v180, 0x48000, v180
	global_load_dwordx4 v[104:107], v180, s[10:11]
.Lmy_stage_3_b:
	v_mfma_f32_32x32x16_bf16 v[16:31], v[32:35], v[122:125], v[16:31]
	v_max3_f32 v32, v64, v65, v66
	v_max3_f32 v33, v48, v49, v50
	v_max3_f32 v32, v32, v67, v68
	v_max3_f32 v33, v33, v51, v52
	v_max3_f32 v32, v32, v69, v70
	v_max3_f32 v33, v33, v53, v54
	v_max3_f32 v32, v32, v71, v72
	v_mfma_f32_32x32x16_bf16 v[16:31], v[36:39], v[126:129], v[16:31]
	v_max3_f32 v33, v33, v55, v56
	v_max3_f32 v32, v32, v73, v74
	v_max3_f32 v33, v33, v57, v58
	v_max3_f32 v32, v32, v75, v76
	v_max3_f32 v33, v33, v59, v60
	v_max_f32_e32 v34, v63, v63
	v_max_f32_e32 v35, v79, v79
	v_mfma_f32_32x32x16_bf16 v[16:31], v[40:43], v[130:133], v[16:31]
	v_max3_f32 v32, v32, v77, v78
	v_max3_f32 v33, v33, v61, v62
	v_max_f32_e32 v34, v35, v34
	v_max3_f32 v32, v32, v33, v34
	v_mov_b32_e32 v33, v32
	s_nop 1
	v_permlane32_swap_b32_e32 v32, v33
	v_mfma_f32_32x32x16_bf16 v[16:31], v[44:47], v[134:137], v[16:31]
	v_max_f32_e32 v33, v33, v33
	v_max_f32_e32 v32, v32, v32
	v_max_f32_e32 v32, v32, v33
	v_cmp_ge_f32_e32 vcc, s78, v32
	s_cmp_eq_u64 vcc, exec
	s_cbranch_scc0 .LBB0_736
	v_mov_b32_e32 v159, 1.0

; __device__ __forceinline__ void finishSM(f32x16& p0, f32x16& p1, float alpha, float& l_reg, bf16x8& pa0, bf16x8& pa1, bf16x8& pa2, bf16x8& pa3) {
; #pragma unroll
;   for (int r = 0; r < 16; ++r) p1[r] = __builtin_amdgcn_exp2f(p1[r]);
;   typedef float f2_t __attribute__((ext_vector_type(2)));
;   f2_t s2a = {p0[0], p0[1]}, s2b = {p1[0], p1[1]};
; #pragma unroll
;   for (int r = 2; r < 16; r += 2) { s2a += (f2_t){p0[r], p0[r + 1]}; s2b += (f2_t){p1[r], p1[r + 1]}; }
;   s2a += s2b; float ps = s2a.x + s2a.y;
;   { auto rr = __builtin_amdgcn_permlane32_swap(__float_as_uint(ps), __float_as_uint(ps), false, false);
;     ps = __uint_as_float(rr[0]) + __uint_as_float(rr[1]); }
;   l_reg = l_reg * alpha + ps;
;     ...
;   PK4(p0, 0, pa0); PK4(p0, 8, pa1); PK4(p1, 0, pa2); PK4(p1, 8, pa3);
;     ...
; }
; __device__ __forceinline__ void qkt(f32x16& p0, f32x16& p1, const char* Ks, const bf16x8* qr, int r32, int hi, float m_reg) {
; #pragma unroll
;   for (int r = 0; r < 16; ++r) { p0[r] = -m_reg; p1[r] = -m_reg; }
; #pragma unroll
;   for (int d0 = 0; d0 < 6; ++d0) { int cb = (d0 * 16 + hi * 8) * 2;
;     bf16x8 b0 = *reinterpret_cast<const bf16x8*>(Ks + KSWZ(r32, cb));
;     bf16x8 b1 = *reinterpret_cast<const bf16x8*>(Ks + KSWZ(32 + r32, cb));
;     p0 = __builtin_amdgcn_mfma_f32_32x32x16_bf16(b0, qr[d0], p0, 0, 0, 0);
;     p1 = __builtin_amdgcn_mfma_f32_32x32x16_bf16(b1, qr[d0], p1, 0, 0, 0); }
; }
; __device__ __forceinline__ int v_st(int k, int c) { const int kk = (k & ~0xC) | ((k & 4) << 1) | ((k & 8) >> 1); return ((kk >> 3) * 4 + (c >> 5)) * 512 + ((kk & 7) * 32 + (c & 31)) * 2; }
; __device__ __forceinline__ int v_rd_base(int lane) { return ((lane & 3) << 3) | (((lane >> 2) & 3) << 6) | (((lane >> 4) & 1) << 5) | (((lane >> 5) & 1) << 8); }
; template <int OFF> __device__ __forceinline__ s16x4 tr_read(int vb) {
;   s16x4 r; asm volatile("ds_read_b64_tr_b16 %0, %1 offset:%2" : "=&v"(r) : "v"(vb), "i"(OFF) : "memory"); return r;
; }
; template <int D0> __device__ __forceinline__ void pv_one(f32x16& od, int vb, bf16x8 pa0, bf16x8 pa1, bf16x8 pa2, bf16x8 pa3) {
;   const s16x4 l0 = tr_read<v_rd_off(D0, 0, 0)>(vb), h0 = tr_read<v_rd_off(D0, 0, 1)>(vb), l1 = tr_read<v_rd_off(D0, 1, 0)>(vb), h1 = tr_read<v_rd_off(D0, 1, 1)>(vb);
.LBB0_724:
	v_exp_f32_e32 v124, v64
	v_exp_f32_e32 v125, v65
	v_exp_f32_e32 v128, v66
	v_exp_f32_e32 v129, v67
	v_exp_f32_e32 v132, v68
	v_exp_f32_e32 v133, v69
	v_exp_f32_e32 v136, v70
	v_exp_f32_e32 v137, v71
	v_exp_f32_e32 v122, v72
	v_exp_f32_e32 v123, v73
	v_exp_f32_e32 v126, v74
	v_exp_f32_e32 v127, v75
	v_exp_f32_e32 v130, v76
	v_exp_f32_e32 v131, v77
	v_exp_f32_e32 v134, v78
	v_exp_f32_e32 v135, v79
	s_waitcnt lgkmcnt(0)
	s_barrier
	v_add_u32_e32 v64, s14, v150
	ds_read_b128 v[168:171], v64 offset:49152
	ds_read_b128 v[172:175], v64 offset:57344
	v_xor_b32_e32 v32, 0x80000000, v154
	v_mov_b32_e32 v33, v32
	v_mov_b32_e32 v34, v32
	v_mov_b32_e32 v35, v32
	v_mov_b32_e32 v36, v32
	v_mov_b32_e32 v37, v32
	v_mov_b32_e32 v38, v32
	v_mov_b32_e32 v39, v32
	v_mov_b32_e32 v40, v32
	v_mov_b32_e32 v41, v32
	v_mov_b32_e32 v42, v32
	v_mov_b32_e32 v43, v32
	v_mov_b32_e32 v44, v32
	v_mov_b32_e32 v45, v32
	v_mov_b32_e32 v46, v32
	v_mov_b32_e32 v47, v32
	v_add_u32_e32 v158, s14, v148
	v_exp_f32_e32 v162, v48
	s_waitcnt lgkmcnt(1)
	v_mfma_f32_32x32x16_bf16 v[64:79], v[168:171], v[92:95], v[32:47]
	v_exp_f32_e32 v163, v49
	v_exp_f32_e32 v176, v58
	v_exp_f32_e32 v177, v59
	v_pk_add_f32 v[48:49], v[128:129], v[124:125]
	v_exp_f32_e32 v178, v60
	v_exp_f32_e32 v179, v61
	v_pk_add_f32 v[48:49], v[132:133], v[48:49]
	s_waitcnt lgkmcnt(0)
	v_mfma_f32_32x32x16_bf16 v[32:47], v[172:175], v[92:95], v[32:47]
	ds_read_b128 v[168:171], v158 offset:49152
	ds_read_b128 v[172:175], v158 offset:57344
	v_add_u32_e32 v158, s14, v147
	v_exp_f32_e32 v62, v62
	v_exp_f32_e32 v63, v63
	v_pk_add_f32 v[48:49], v[136:137], v[48:49]
	s_nop 0
	v_pk_add_f32 v[48:49], v[122:123], v[48:49]
	s_waitcnt lgkmcnt(1)
	v_mfma_f32_32x32x16_bf16 v[64:79], v[168:171], v[88:91], v[64:79]
	v_add_f32_e64 v48, v126, v48
	v_add_f32_e64 v49, v127, v49
	v_add_f32_e64 v48, v130, v48
	v_add_f32_e64 v49, v131, v49
	v_add_f32_e64 v48, v134, v48
	v_add_f32_e64 v49, v135, v49
	s_waitcnt lgkmcnt(0)
	v_mfma_f32_32x32x16_bf16 v[32:47], v[172:175], v[88:91], v[32:47]
	ds_read_b128 v[168:171], v158 offset:49152
	ds_read_b128 v[172:175], v158 offset:57344
	v_add_u32_e32 v158, s14, v146
	s_waitcnt lgkmcnt(1)
	v_mfma_f32_32x32x16_bf16 v[64:79], v[168:171], v[84:87], v[64:79]
	s_waitcnt lgkmcnt(0)
	v_mfma_f32_32x32x16_bf16 v[32:47], v[172:175], v[84:87], v[32:47]
	ds_read_b128 v[168:171], v158 offset:49152
	ds_read_b128 v[172:175], v158 offset:57344
	v_add_u32_e32 v158, s14, v144
	s_waitcnt lgkmcnt(1)
	v_mfma_f32_32x32x16_bf16 v[64:79], v[168:171], v[80:83], v[64:79]
	s_waitcnt lgkmcnt(0)
	v_mfma_f32_32x32x16_bf16 v[32:47], v[172:175], v[80:83], v[32:47]
	ds_read_b128 v[168:171], v158 offset:49152
	ds_read_b128 v[172:175], v158 offset:57344
	v_add_u32_e32 v158, s14, v143
	s_waitcnt lgkmcnt(1)
	v_mfma_f32_32x32x16_bf16 v[64:79], v[168:171], v[96:99], v[64:79]
	s_waitcnt lgkmcnt(0)
	v_mfma_f32_32x32x16_bf16 v[32:47], v[172:175], v[96:99], v[32:47]
	ds_read_b128 v[168:171], v158 offset:49152
	ds_read_b128 v[172:175], v158 offset:57344
	s_waitcnt lgkmcnt(1)
	v_mfma_f32_32x32x16_bf16 v[64:79], v[168:171], v[100:103], v[64:79]
	v_exp_f32_e32 v168, v50
	v_exp_f32_e32 v169, v51
	v_exp_f32_e32 v170, v52
	v_exp_f32_e32 v171, v53
	v_pk_add_f32 v[50:51], v[162:163], v[168:169]
	s_nop 0
	v_pk_add_f32 v[50:51], v[170:171], v[50:51]
	s_waitcnt lgkmcnt(0)
	v_mfma_f32_32x32x16_bf16 v[32:47], v[172:175], v[100:103], v[32:47]
	v_exp_f32_e32 v172, v54
	v_exp_f32_e32 v173, v55
	v_exp_f32_e32 v174, v56
	v_exp_f32_e32 v175, v57
	v_pk_add_f32 v[50:51], v[172:173], v[50:51]
	s_nop 0
	v_pk_add_f32 v[50:51], v[174:175], v[50:51]
	s_nop 0
	v_pk_add_f32 v[50:51], v[176:177], v[50:51]
	s_nop 0
	v_pk_add_f32 v[50:51], v[178:179], v[50:51]
	s_nop 0
	v_pk_add_f32 v[50:51], v[62:63], v[50:51]
	s_nop 0
	v_pk_add_f32 v[48:49], v[48:49], v[50:51]
	v_cvt_pk_bf16_f32 v50, v124, v125
	v_cvt_pk_bf16_f32 v51, v128, v129
	v_cvt_pk_bf16_f32 v52, v132, v133
	v_cvt_pk_bf16_f32 v53, v136, v137
	v_cvt_pk_bf16_f32 v54, v122, v123
	s_nop 0
	v_pk_add_f32 v[48:49], v[48:49], v[48:49] op_sel:[0,1] op_sel_hi:[1,0]
	v_permlane32_swap_b32_e32 v50, v52
	v_mov_b32_e32 v49, v48
	s_nop 1
	v_permlane32_swap_b32_e32 v48, v49
	v_cvt_pk_bf16_f32 v55, v126, v127
	v_cvt_pk_bf16_f32 v56, v130, v131
	v_cvt_pk_bf16_f32 v57, v134, v135
	v_cvt_pk_bf16_f32 v58, v162, v163
	v_cvt_pk_bf16_f32 v59, v168, v169
	v_cvt_pk_bf16_f32 v60, v170, v171
	v_cvt_pk_bf16_f32 v61, v172, v173
	v_cvt_pk_bf16_f32 v122, v174, v175
	v_cvt_pk_bf16_f32 v123, v176, v177
	v_cvt_pk_bf16_f32 v124, v178, v179
	v_cvt_pk_bf16_f32 v125, v62, v63
	v_permlane32_swap_b32_e32 v51, v53
	v_permlane32_swap_b32_e32 v54, v56
	v_permlane32_swap_b32_e32 v55, v57
	v_permlane32_swap_b32_e32 v58, v60
	v_permlane32_swap_b32_e32 v59, v61
	v_permlane32_swap_b32_e32 v122, v124
	v_permlane32_swap_b32_e32 v123, v125
	v_add_u32_e32 v62, s24, v142
	ds_read_b64_tr_b16 v[126:127], v62 offset:0
	ds_read_b64_tr_b16 v[128:129], v62 offset:0x800
	ds_read_b64_tr_b16 v[130:131], v62 offset:0x1000
	ds_read_b64_tr_b16 v[132:133], v62 offset:0x1800
	ds_read_b64_tr_b16 v[134:135], v62 offset:0x2000
	ds_read_b64_tr_b16 v[136:137], v62 offset:0x2800
	ds_read_b64_tr_b16 v[168:169], v62 offset:0x3000
	ds_read_b64_tr_b16 v[170:171], v62 offset:0x3800
	s_waitcnt lgkmcnt(0)
	s_nop 0
	v_mfma_f32_32x32x16_bf16 v[0:15], v[50:53], v[126:129], v[0:15]
	ds_read_b64_tr_b16 v[126:127], v62 offset:0x200
	ds_read_b64_tr_b16 v[128:129], v62 offset:0xa00
	v_mfma_f32_32x32x16_bf16 v[0:15], v[54:57], v[130:133], v[0:15]
	ds_read_b64_tr_b16 v[130:131], v62 offset:0x1200
	ds_read_b64_tr_b16 v[132:133], v62 offset:0x1a00
	v_mfma_f32_32x32x16_bf16 v[0:15], v[58:61], v[134:137], v[0:15]
	ds_read_b64_tr_b16 v[134:135], v62 offset:0x2200
	ds_read_b64_tr_b16 v[136:137], v62 offset:0x2a00
	v_mfma_f32_32x32x16_bf16 v[0:15], v[122:125], v[168:171], v[0:15]
	ds_read_b64_tr_b16 v[168:169], v62 offset:0x3200
	ds_read_b64_tr_b16 v[170:171], v62 offset:0x3a00
	s_waitcnt lgkmcnt(0)
	v_add_u32_e32 v180, s87, v153
	s_add_i32 s25, s87, 0
	s_waitcnt vmcnt(1)
	ds_write_b128 v180, v[112:115]
	v_add_u32_e32 v180, s25, v151
	s_and_b64 vcc, exec, s[8:9]
	s_waitcnt vmcnt(0)
	ds_write_b128 v180, v[108:111] offset:49152
	s_cbranch_vccnz .Lmy_stage_2_a
	v_add_u32_e32 v180, s25, v152
	ds_write_b128 v180, v[104:107] offset:49152
; template <bool FIRST>
; __device__ __forceinline__ void partialSM(f32x16& p0, f32x16& p1, float& m_reg, float& alpha) {
;   float a = fmaxf(fmaxf(p0[0], p0[1]), p0[2]), b = fmaxf(fmaxf(p1[0], p1[1]), p1[2]);
; #pragma unroll
;   for (int r = 3; r < 15; r += 2) { a = fmaxf(fmaxf(a, p0[r]), p0[r + 1]); b = fmaxf(fmaxf(b, p1[r]), p1[r + 1]); }
;   float pmax = fmaxf(fmaxf(a, b), fmaxf(p0[15], p1[15]));
;   { auto rr = __builtin_amdgcn_permlane32_swap(__float_as_uint(pmax), __float_as_uint(pmax), false, false);
;     pmax = fmaxf(__uint_as_float(rr[0]), __uint_as_float(rr[1])); }
;   alpha = 1.f;
;   if (FIRST || !__builtin_expect(__all(pmax <= THRL), 1)) {
.Lmy_stage_2_a:
	s_cmpk_gt_u32 s81, 0x7c
	s_cselect_b64 s[4:5], -1, 0
	s_and_b64 vcc, exec, s[4:5]
	s_cbranch_vccnz .Lmy_stage_2_b
	v_add_u32_e32 v180, 0x60000, v160
	global_load_dwordx4 v[112:115], v155, s[12:13]
	global_load_dwordx4 v[108:111], v180, s[10:11]
	s_and_b64 vcc, exec, s[8:9]
	s_cbranch_vccnz .Lmy_stage_2_b
	v_add_u32_e32 v180, s80, v149
	v_add_u32_e32 v180, 0x60000, v180
	global_load_dwordx4 v[104:107], v180, s[10:11]
.Lmy_stage_2_b:
	v_mfma_f32_32x32x16_bf16 v[16:31], v[50:53], v[126:129], v[16:31]
	v_max3_f32 v50, v64, v65, v66
	v_max3_f32 v51, v32, v33, v34
	v_max3_f32 v50, v50, v67, v68
	v_max3_f32 v51, v51, v35, v36
	v_max3_f32 v50, v50, v69, v70
	v_max3_f32 v51, v51, v37, v38
	v_max3_f32 v50, v50, v71, v72
	v_mfma_f32_32x32x16_bf16 v[16:31], v[54:57], v[130:133], v[16:31]
	v_max3_f32 v51, v51, v39, v40
	v_max3_f32 v50, v50, v73, v74
	v_max3_f32 v51, v51, v41, v42
	v_max3_f32 v50, v50, v75, v76
	v_max3_f32 v51, v51, v43, v44
	v_max_f32_e32 v52, v47, v47
	v_max_f32_e32 v53, v79, v79
	v_mfma_f32_32x32x16_bf16 v[16:31], v[58:61], v[134:137], v[16:31]
	v_max3_f32 v50, v50, v77, v78
	v_max3_f32 v51, v51, v45, v46
	v_max_f32_e32 v52, v53, v52
	v_max3_f32 v50, v50, v51, v52
	v_mov_b32_e32 v51, v50
	s_nop 1
	v_permlane32_swap_b32_e32 v50, v51
	v_mfma_f32_32x32x16_bf16 v[16:31], v[122:125], v[168:171], v[16:31]
	v_max_f32_e32 v51, v51, v51
	v_max_f32_e32 v50, v50, v50
	v_max_f32_e32 v50, v50, v51
	v_cmp_ge_f32_e32 vcc, s78, v50
	s_cmp_eq_u64 vcc, exec
	v_mov_b32_e32 v158, 1.0
	s_cbranch_scc0 .LBB0_737

; #define LAS __attribute__((address_space(3)))
; __device__ __forceinline__ unsigned pkbf(float lo, float hi) { return pg8::cvt_pk_bf16(lo, hi); }
; __device__ __forceinline__ void scan_fix_item(const P& p, LAS unsigned char* lds, int hd, int blk) {
;     ...
;     const float* smid = (const float*)(ws + WS_SMID) + (size_t)hd * 4096;
;     const float* qc = (const float*)(ws + (hd < 12 ? WS_QC0 + (size_t)hd * 2 * MiB : WS_QC1 + (size_t)(hd - 12) * 2 * MiB)) + (size_t)blk * 128 * 64;
;     bf16_t* Yd = (bf16_t*)(ws + WS_Y) + ((hd & 1) ? (size_t)T * 512 : 0);
;     LAS float* lq = (LAS float*)lds;
;     for (int i = tid; i < 128 * 16; i += 512) *(LAS f32x4*)(lq + i * 4) = *(const f32x4*)(qc + i * 4);
;     f32x4 sm[16];
; #pragma unroll
;     for (int i = 0; i < 16; ++i) sm[i] = *(const f32x4*)(smid + lane * 64 + i * 4);
;     __syncthreads();
;     const int head = hd >> 1, dir = hd & 1;
;     for (int s = 0; s < 16; ++s) {
;         const int j = wave * 16 + s; LAS const float* q = lq + j * 64;
;         float a0 = 0.f, a1 = 0.f, a2 = 0.f, a3 = 0.f;
; #pragma unroll
;         for (int i = 0; i < 16; ++i) { const f32x4 qv = *(LAS const f32x4*)(q + i * 4); a0 = fmaf(sm[i][0], qv[0], a0); a1 = fmaf(sm[i][1], qv[1], a1); a2 = fmaf(sm[i][2], qv[2], a2); a3 = fmaf(sm[i][3], qv[3], a3); }
;         const int jj = blk * 128 + j; const int t = dir ? (8191 - jj) : (8192 + jj);
;         bf16_t* yg = Yd + (size_t)(TP + t) * 512 + head * 64 + lane;
;         const float yv = __uint_as_float((unsigned)*yg << 16) + ((a0 + a1) + (a2 + a3));
;         *yg = (bf16_t)(pkbf(yv, yv) & 0xffffu);
.LBB0_1112:
	s_or_b64 exec, exec, s[0:1]
	s_and_b32 s0, s13, 63
	s_lshl_b32 s7, s0, 7
	s_lshl_b64 s[0:1], s[4:5], 14
	v_and_b32_e32 v64, 63, v2
	s_add_u32 s0, s50, s0
	s_addc_u32 s1, s51, s1
	v_lshlrev_b32_e32 v60, 8, v64
	global_load_dwordx4 v[0:3], v60, s[0:1] offset:240
	global_load_dwordx4 v[4:7], v60, s[0:1] offset:224
	global_load_dwordx4 v[8:11], v60, s[0:1] offset:208
	global_load_dwordx4 v[12:15], v60, s[0:1] offset:192
	global_load_dwordx4 v[16:19], v60, s[0:1] offset:176
	global_load_dwordx4 v[20:23], v60, s[0:1] offset:160
	global_load_dwordx4 v[24:27], v60, s[0:1] offset:144
	global_load_dwordx4 v[28:31], v60, s[0:1] offset:128
	global_load_dwordx4 v[32:35], v60, s[0:1] offset:112
	global_load_dwordx4 v[36:39], v60, s[0:1] offset:96
	global_load_dwordx4 v[40:43], v60, s[0:1] offset:80
	global_load_dwordx4 v[44:47], v60, s[0:1] offset:64
	global_load_dwordx4 v[48:51], v60, s[0:1] offset:48
	global_load_dwordx4 v[52:55], v60, s[0:1] offset:32
	global_load_dwordx4 v[56:59], v60, s[0:1] offset:16
	s_nop 0
	global_load_dwordx4 v[60:63], v60, s[0:1]
	s_and_b32 s0, s86, 64
	s_bfe_i32 s5, s86, 0x10006
	s_cmp_eq_u32 s0, 0
	s_cselect_b64 s[0:1], -1, 0
	s_and_b32 s5, s5, 0x3000000
	s_add_u32 s8, s84, s5
	s_addc_u32 s9, s85, 0
	s_lshl_b32 s4, s4, 5
	s_andn2_b32 s4, s4, 63
	s_ashr_i32 s14, s14, 2
	s_ashr_i32 s5, s4, 31
	s_and_b32 s15, s14, -16
	s_lshl_b64 s[4:5], s[4:5], 1
	s_add_u32 s4, s8, s4
	v_lshlrev_b32_e32 v102, 1, v64
	s_addc_u32 s5, s9, s5
	v_lshl_add_u64 v[104:105], s[4:5], 0, v[102:103]
	s_lshl_b32 s4, s14, 8
	s_add_i32 s7, s7, s15
	s_and_b32 s4, s4, 0xfffff000
	s_mov_b32 s6, 0
	s_sub_i32 s8, 0x1ffe, s7
	s_add_i32 s9, s4, 0
	s_waitcnt lgkmcnt(0)
	s_barrier
	s_waitcnt vmcnt(15)
	v_mov_b32_e32 v106, v1
	v_mov_b32_e32 v107, v2
	s_waitcnt vmcnt(14)
	v_mov_b32_e32 v108, v5
	v_mov_b32_e32 v109, v6
	s_waitcnt vmcnt(13)
	v_mov_b32_e32 v110, v9
	v_mov_b32_e32 v111, v10
	s_waitcnt vmcnt(12)
	v_mov_b32_e32 v112, v13
	v_mov_b32_e32 v113, v14
	s_waitcnt vmcnt(11)
	v_mov_b32_e32 v114, v17
	v_mov_b32_e32 v115, v18
	s_waitcnt vmcnt(10)
	v_mov_b32_e32 v116, v21
	v_mov_b32_e32 v117, v22
	s_waitcnt vmcnt(9)
	v_mov_b32_e32 v118, v25
	v_mov_b32_e32 v119, v26
	s_waitcnt vmcnt(8)
	v_mov_b32_e32 v120, v29
	v_mov_b32_e32 v121, v30
	s_waitcnt vmcnt(7)
	v_mov_b32_e32 v122, v33
	v_mov_b32_e32 v123, v34
	s_waitcnt vmcnt(6)
	v_mov_b32_e32 v124, v37
	v_mov_b32_e32 v125, v38
	s_waitcnt vmcnt(5)
	v_mov_b32_e32 v126, v41
	v_mov_b32_e32 v127, v42
	v_mov_b32_e32 v1, v3
	v_mov_b32_e32 v5, v7
	v_mov_b32_e32 v9, v11
	v_mov_b32_e32 v13, v15
	v_mov_b32_e32 v17, v19
	v_mov_b32_e32 v21, v23
	v_mov_b32_e32 v25, v27
	v_mov_b32_e32 v29, v31
	v_mov_b32_e32 v33, v35
	v_mov_b32_e32 v37, v39
	v_mov_b32_e32 v41, v43
	s_waitcnt vmcnt(4)
	v_mov_b32_e32 v2, v44
	v_mov_b32_e32 v3, v47
	s_waitcnt vmcnt(3)
	v_mov_b32_e32 v6, v48
	v_mov_b32_e32 v7, v51
	s_waitcnt vmcnt(2)
	v_mov_b32_e32 v10, v52
	v_mov_b32_e32 v11, v55
	s_waitcnt vmcnt(1)
	v_mov_b32_e32 v14, v56
	v_mov_b32_e32 v15, v59
	s_waitcnt vmcnt(0)
	v_mov_b32_e32 v18, v60
	v_mov_b32_e32 v19, v63
	v_mov_b32_e32 v22, v45
	v_mov_b32_e32 v23, v46
	v_mov_b32_e32 v26, v49
	v_mov_b32_e32 v27, v50
	v_mov_b32_e32 v30, v53
	v_mov_b32_e32 v31, v54
	v_mov_b32_e32 v34, v57
	v_mov_b32_e32 v35, v58
	v_mov_b32_e32 v38, v61
	v_mov_b32_e32 v39, v62
	s_add_i32 s14, s7, 0x2000
	s_add_i32 s15, s8, 1
	s_and_b64 s[4:5], s[0:1], exec
	s_cselect_b32 s14, s14, s15
	s_mov_b32 s16, 0xfffffc00
	s_cselect_b32 s4, 0x400, s16
	s_ashr_i32 s15, s14, 31
	s_lshl_b64 s[14:15], s[14:15], 10
	s_add_u32 s14, s14, s12
	s_addc_u32 s15, s15, 0
	s_ashr_i32 s5, s4, 31
	v_lshl_add_u64 v[160:161], v[104:105], 0, s[14:15]
	global_load_ushort v144, v[160:161], off
	v_lshl_add_u64 v[160:161], v[160:161], 0, s[4:5]
	global_load_ushort v145, v[160:161], off
	v_lshl_add_u64 v[160:161], v[160:161], 0, s[4:5]
	global_load_ushort v146, v[160:161], off
	v_lshl_add_u64 v[160:161], v[160:161], 0, s[4:5]
	global_load_ushort v147, v[160:161], off
	v_lshl_add_u64 v[160:161], v[160:161], 0, s[4:5]
	global_load_ushort v148, v[160:161], off
	v_lshl_add_u64 v[160:161], v[160:161], 0, s[4:5]
	global_load_ushort v149, v[160:161], off
	v_lshl_add_u64 v[160:161], v[160:161], 0, s[4:5]
	global_load_ushort v150, v[160:161], off
	v_lshl_add_u64 v[160:161], v[160:161], 0, s[4:5]
	global_load_ushort v151, v[160:161], off
	v_lshl_add_u64 v[160:161], v[160:161], 0, s[4:5]
	global_load_ushort v152, v[160:161], off
	v_lshl_add_u64 v[160:161], v[160:161], 0, s[4:5]
	global_load_ushort v153, v[160:161], off
	v_lshl_add_u64 v[160:161], v[160:161], 0, s[4:5]
	global_load_ushort v154, v[160:161], off
	v_lshl_add_u64 v[160:161], v[160:161], 0, s[4:5]
	global_load_ushort v155, v[160:161], off
	v_lshl_add_u64 v[160:161], v[160:161], 0, s[4:5]
	global_load_ushort v156, v[160:161], off
	v_lshl_add_u64 v[160:161], v[160:161], 0, s[4:5]
	global_load_ushort v157, v[160:161], off
	v_lshl_add_u64 v[160:161], v[160:161], 0, s[4:5]
	global_load_ushort v158, v[160:161], off
	v_lshl_add_u64 v[160:161], v[160:161], 0, s[4:5]
	global_load_ushort v159, v[160:161], off
